# diff attention: last 16-key slice of each tile (8 exp, sums, 4 cvt, 4 PV MFMAs) deferred into the next tile's QK phase; QK key-half 0 first
# speedup vs baseline: 1.0027x; 1.0027x over previous
; #define ATT_LOAD(S, j) do { rk##S = *(const u32x4*)(ksrc + (size_t)(j) * 64 * 1024); if (!DIFF && tid < 256) rk2##S = *(const u32x4*)(k2src + (size_t)(j) * 64 * 32); \
;         rv0##S = *(const u32x4*)(vsrc + (size_t)(j) * 64 * 1024); if (DIFF) rv1##S = *(const u32x4*)(vsrc + (size_t)(j) * 64 * 1024 + 32 * 1024); } while (0)
; #define ATT_STORE(S, bufp) do { *(LAS u32x4*)((bufp) + kdst) = rk##S; if (!DIFF && tid < 256) *(LAS u32x4*)((bufp) + k2dst) = rk2##S; \
;         *(LAS u32x4*)((bufp) + vdst) = rv0##S; if (DIFF) *(LAS u32x4*)((bufp) + vdst + 32 * PV) = rv1##S; } while (0)
; template <bool DIFF>
; __device__ __forceinline__ void attn_unit_coop(const Grp& G, int b, int h, int qb, int n, LAS unsigned char* lds, const int tid_in) {
;     ...
;         AttnState<DQK, DV> st; attn_init(st);
;         if (DIFF) { const bf16* qp = G.QD + (seq0 + qrow0 + q) * 1024 + h * 128 + n * 64 + hi * 8;
; #pragma unroll
;             for (int ks = 0; ks < 4; ++ks) st.qf[ks] = *(const bf16x8*)(qp + ks * 16);
;         } else { const bf16* qn = G.QN + (seq0 + qrow0 + q) * 1024 + h * 64 + hi * 8; const bf16* qr = G.QR + (seq0 + qrow0 + q) * 512 + h * 32 + hi * 8;
; #pragma unroll
;             for (int ks = 0; ks < 4; ++ks) st.qf[ks] = *(const bf16x8*)(qn + ks * 16);
; #pragma unroll
;             for (int ks = 0; ks < 2; ++ks) st.qf[4 + ks] = *(const bf16x8*)(qr + ks * 16);
;         }
;         const bf16* ksrc = (DIFF ? G.KD + h * 128 + n * 64 : G.KN + h * 64) + (seq0 + (tid >> 3)) * 1024 + (tid & 7) * 8;
;         const int kdst = (tid >> 3) * PK + (tid & 7) * 16;
;         const bf16* k2src = G.KR + (seq0 + ((tid & 255) >> 2)) * 32 + (tid & 3) * 8;
;         const int k2dst = ((tid & 255) >> 2) * PK + 128 + (tid & 3) * 16;
;         const bf16* vsrc = DIFF ? G.VD + (seq0 + (tid >> 4)) * 1024 + h * 128 + (tid & 15) * 8 : G.VM + (seq0 + (tid >> 3)) * 1024 + h * 64 + (tid & 7) * 8;
;         const int vdst = DIFF ? KB + (tid >> 4) * PV + (tid & 15) * 16 : KB + (tid >> 3) * PV + (tid & 7) * 16;
;         u32x4 rkA, rk2A = {0u, 0u, 0u, 0u}, rv0A, rv1A = {0u, 0u, 0u, 0u}, rkB = {0u, 0u, 0u, 0u}, rk2B = {0u, 0u, 0u, 0u}, rv0B = {0u, 0u, 0u, 0u}, rv1B = {0u, 0u, 0u, 0u};
;     ...
;         ATT_LOAD(A, 0); ATT_STORE(A, tiles);
;         __syncthreads();
;         ATT_LOAD(A, 1);
.LBB0_519:
	v_mov_b32_e32 v28, v212
	v_mov_b32_e32 v15, v185
	v_ashrrev_i32_e32 v12, 3, v28
	v_ashrrev_i32_e32 v13, 31, v12
	v_lshl_add_u64 v[0:1], s[24:25], 0, v[12:13]
	v_lshlrev_b64 v[0:1], 11, v[0:1]
	v_lshlrev_b32_e32 v2, 4, v28
	v_ashrrev_i32_e32 v18, 4, v28
	v_lshl_add_u64 v[0:1], s[30:31], 0, v[0:1]
	v_and_b32_e32 v14, 0x70, v2
	v_ashrrev_i32_e32 v19, 31, v18
	v_lshl_add_u64 v[16:17], v[0:1], 0, v[14:15]
	v_lshl_add_u64 v[0:1], s[24:25], 0, v[18:19]
	v_lshlrev_b64 v[0:1], 11, v[0:1]
	v_lshl_add_u64 v[0:1], s[14:15], 0, v[0:1]
	v_and_b32_e32 v20, 0xf0, v2
	v_mov_b32_e32 v21, v185
	v_lshl_add_u64 v[22:23], v[0:1], 0, v[20:21]
	global_load_dwordx4 v[0:3], v[16:17], off
	global_load_dwordx4 v[4:7], v[22:23], off
	v_add_co_u32_e32 v8, vcc, s53, v22
	s_xor_b64 s[36:37], s[0:1], -1
	s_nop 0
	v_addc_co_u32_e32 v9, vcc, 0, v23, vcc
	global_load_dwordx4 v[8:11], v[8:9], off
	s_and_b64 s[0:1], s[0:1], exec
	s_cselect_b32 s0, s48, s90
	v_readfirstlane_b32 s1, v28
	s_lshl_b32 s2, s0, 8
	s_ashr_i32 s3, s1, 1
	s_lshl_b32 s7, s0, 2
	s_ashr_i32 s40, s1, 7
	s_and_b32 s41, s1, 0x3fffffc0
	v_mad_u64_u32 v[24:25], s[0:1], v12, s76, v[14:15]
	s_andn2_b32 s3, s3, 31
	s_movk_i32 s0, 0x140
	v_mad_u64_u32 v[26:27], s[0:1], v18, s0, v[20:21]
	s_add_i32 s42, s3, s2
	s_ashr_i32 s0, s42, 31
	s_add_u32 s38, s24, s42
	v_and_b32_e32 v194, 31, v28
	s_addc_u32 s39, s25, s0
	v_add_u32_e32 v214, 0, v24
	v_or_b32_e32 v24, s38, v194
	v_add_co_u32_e32 v16, vcc, s62, v16
	v_mov_b32_e32 v25, s39
	v_bfe_u32 v191, v28, 5, 1
	v_addc_co_u32_e32 v17, vcc, 0, v17, vcc
	v_lshlrev_b64 v[24:25], 11, v[24:25]
	v_lshlrev_b32_e32 v184, 4, v191
	v_add_u32_e32 v215, 0, v26
	v_add_co_u32_e32 v26, vcc, s62, v22
	v_lshl_add_u64 v[24:25], s[28:29], 0, v[24:25]
	s_nop 0
	v_addc_co_u32_e32 v27, vcc, 0, v23, vcc
	s_mov_b32 s0, 0x30000
	v_lshl_add_u64 v[24:25], v[24:25], 0, v[184:185]
	v_add_co_u32_e32 v22, vcc, s0, v22
	global_load_dwordx4 v[112:115], v[24:25], off
	global_load_dwordx4 v[116:119], v[24:25], off offset:32
	global_load_dwordx4 v[120:123], v[24:25], off offset:64
	global_load_dwordx4 v[124:127], v[24:25], off offset:96
	v_addc_co_u32_e32 v23, vcc, 0, v23, vcc
	s_lshl_b32 s0, s41, 2
	s_add_i32 s6, s7, 4
	s_add_i32 s7, s40, s7
	s_add_i32 s40, s0, 0
	v_mov_b32_e32 v142, v185
	v_mov_b32_e32 v143, v185
	v_mov_b32_e32 v48, v185
	v_mov_b32_e32 v49, v185
	v_mov_b32_e32 v62, v185
	v_mov_b32_e32 v63, v185
	v_mov_b32_e32 v140, v185
	v_mov_b32_e32 v141, v185
	v_mov_b32_e32 v50, v185
	v_mov_b32_e32 v51, v185
	v_mov_b32_e32 v52, v185
	v_mov_b32_e32 v53, v185
	v_mov_b32_e32 v54, v185
	v_mov_b32_e32 v55, v185
	v_mov_b32_e32 v56, v185
	v_mov_b32_e32 v57, v185
	v_mov_b32_e32 v58, v185
	v_mov_b32_e32 v59, v185
	s_waitcnt vmcnt(6)
	ds_write_b128 v214, v[0:3] offset:8192
	s_waitcnt vmcnt(5)
	ds_write_b128 v215, v[4:7] offset:17408
	s_waitcnt vmcnt(4)
	ds_write_b128 v215, v[8:11] offset:27648
	s_waitcnt lgkmcnt(0)
	s_barrier
	global_load_dwordx4 v[128:131], v[16:17], off
	global_load_dwordx4 v[132:135], v[26:27], off
	global_load_dwordx4 v[136:139], v[22:23], off
	v_and_b32_e32 v0, 63, v28
	v_lshlrev_b32_e32 v1, 2, v191
	v_lshrrev_b32_e32 v3, 2, v28
	v_and_b32_e32 v4, 16, v28
	v_lshlrev_b32_e32 v5, 2, v28
	v_and_or_b32 v4, v5, 12, v4
	v_cmp_gt_u32_e64 s[0:1], 32, v0
	v_and_or_b32 v0, v3, 3, v1
	v_lshlrev_b32_e32 v4, 1, v4
	v_mul_u32_u24_e32 v0, 0x140, v0
	v_add3_u32 v217, 0, v4, v0
	v_or_b32_e32 v0, s42, v194
	v_sub_u32_e32 v218, v1, v0
	v_sub_u32_e32 v0, v1, v194
	v_subrev_u32_e32 v0, s3, v0
	v_subrev_u32_e32 v219, s2, v0
	s_mul_i32 s98, s85, 5
	s_add_i32 s98, s98, 0x11380
	v_lshl_add_u32 v225, v218, 2, s98
	v_lshlrev_b64 v[0:1], 11, v[18:19]
	v_or_b32_e32 v0, v0, v20
	v_lshl_add_u64 v[196:197], s[22:23], 0, v[0:1]
	v_lshlrev_b64 v[0:1], 11, v[12:13]
	v_mad_u32_u24 v2, v194, s76, 0
	v_or_b32_e32 v0, v0, v14
	v_lshl_add_u64 v[198:199], s[34:35], 0, v[0:1]
	v_mov_b32_e32 v60, v185
	v_mov_b32_e32 v61, v185
	v_add_u32_e32 v221, v2, v184
	v_mov_b64_e32 v[32:33], v[48:49]
	v_mov_b64_e32 v[16:17], v[48:49]
	v_mov_b64_e32 v[0:1], v[48:49]
	v_mov_b64_e32 v[78:79], v[62:63]
	v_mov_b64_e32 v[146:147], v[142:143]
	v_mov_b64_e32 v[150:151], v[142:143]
	s_mov_b32 s58, 0
	v_lshl_add_u32 v216, v194, 2, s40
	v_add_u32_e32 v213, s40, v184
	s_sub_i32 s92, 0, s42
	v_mov_b32_e32 v220, 0
	v_mov_b64_e32 v[34:35], v[50:51]
	v_mov_b64_e32 v[36:37], v[52:53]
	v_mov_b64_e32 v[38:39], v[54:55]
	v_mov_b64_e32 v[40:41], v[56:57]
	v_mov_b64_e32 v[42:43], v[58:59]
	v_mov_b64_e32 v[44:45], v[60:61]
	v_mov_b64_e32 v[46:47], v[62:63]
	v_mov_b64_e32 v[18:19], v[50:51]
	v_mov_b64_e32 v[20:21], v[52:53]
	v_mov_b64_e32 v[22:23], v[54:55]
	v_mov_b64_e32 v[24:25], v[56:57]
	v_mov_b64_e32 v[26:27], v[58:59]
	v_mov_b64_e32 v[28:29], v[60:61]
	v_mov_b64_e32 v[30:31], v[62:63]
	v_mov_b64_e32 v[2:3], v[50:51]
	v_mov_b64_e32 v[4:5], v[52:53]
	v_mov_b64_e32 v[6:7], v[54:55]
	v_mov_b64_e32 v[8:9], v[56:57]
	v_mov_b64_e32 v[10:11], v[58:59]
	v_mov_b64_e32 v[12:13], v[60:61]
	v_mov_b64_e32 v[14:15], v[62:63]
	v_mov_b64_e32 v[76:77], v[60:61]
	v_mov_b64_e32 v[74:75], v[58:59]
	v_mov_b64_e32 v[72:73], v[56:57]
	v_mov_b64_e32 v[70:71], v[54:55]
	v_mov_b64_e32 v[68:69], v[52:53]
	v_mov_b64_e32 v[66:67], v[50:51]
	v_mov_b64_e32 v[64:65], v[48:49]
	v_mov_b32_e32 v184, 0
	v_mov_b64_e32 v[144:145], v[140:141]
	v_mov_b64_e32 v[148:149], v[140:141]
	s_mov_b32 s59, 0
	v_mov_b32_e32 v104, 0xf149f2ca
	v_mov_b32_e32 v105, 0xf149f2ca
	v_mov_b32_e32 v106, 0xf149f2ca
	v_mov_b32_e32 v107, 0xf149f2ca
	v_mov_b32_e32 v108, 0xf149f2ca
	v_mov_b32_e32 v109, 0xf149f2ca
	v_mov_b32_e32 v110, 0xf149f2ca
	v_mov_b32_e32 v111, 0xf149f2ca
	v_mov_b32_e32 v226, 0
	v_mov_b32_e32 v227, 0
	v_mov_b32_e32 v228, 0
	v_mov_b32_e32 v229, 0
	v_mov_b32_e32 v230, 0
	v_mov_b32_e32 v231, 0
	v_mov_b32_e32 v232, 0
	v_mov_b32_e32 v233, 0
	v_mov_b32_e32 v234, 0
	v_mov_b32_e32 v235, 0
	v_mov_b32_e32 v236, 0
	v_mov_b32_e32 v237, 0
	v_mov_b32_e32 v238, 0
	v_mov_b32_e32 v239, 0
	v_mov_b32_e32 v240, 0
	v_mov_b32_e32 v241, 0

; #define LAS __attribute__((address_space(3)))
; __device__ __forceinline__ int crow(int r, int hi) { return (r & 3) + 8 * (r >> 2) + 4 * hi; }
; template <int DQK, int DV, bool HAS_BIAS>
; __device__ __forceinline__ void attn_tile(AttnState<DQK, DV>& st, const LAS unsigned char* Kt, const LAS unsigned char* Vt, int bias_mode, const LAS float* tab, int rel0, int nkeys, bool first, LAS float* wsf, int lane) {
;     ...
;     if (HAS_BIAS && bias_mode == 2) {
;         asm volatile("" ::: "memory");
; #pragma unroll
;         for (int r = 0; r < 16; ++r) {
;             const int k = crow(r, hi);
;             const int i0 = min(max(rel0 + k + 128, 0), 191), i1 = min(max(rel0 + k + 160, 0), 191);
;             p0[r] = tab[i0] + st.negm[r]; p1[r] = tab[i1] + st.negm[r];
;         }
;         p0 = __builtin_amdgcn_mfma_f32_32x32x16_bf16(ka[0], st.qf[0], p0, 0, 0, 0);
;         p1 = __builtin_amdgcn_mfma_f32_32x32x16_bf16(kb[0], st.qf[0], p1, 0, 0, 0);
;     } else {
;         p0 = __builtin_amdgcn_mfma_f32_32x32x16_bf16(ka[0], st.qf[0], st.negm, 0, 0, 0);
;         p1 = __builtin_amdgcn_mfma_f32_32x32x16_bf16(kb[0], st.qf[0], st.negm, 0, 0, 0);
;     }
; #pragma unroll
;     for (int ks = 1; ks < KS; ++ks) {
;         p0 = __builtin_amdgcn_mfma_f32_32x32x16_bf16(ka[ks], st.qf[ks], p0, 0, 0, 0);
;         p1 = __builtin_amdgcn_mfma_f32_32x32x16_bf16(kb[ks], st.qf[ks], p1, 0, 0, 0);
;     }
;     const int q4 = (lane & 15) >> 2, blk = (lane >> 4) & 1, pp = lane & 3;
;     const LAS unsigned char* vp = Vt + (4 * hi + q4) * PV + (16 * blk + 4 * pp) * 2;
;     s16x4 vlo[2][4], vhi[2][4];
; #pragma unroll
;     for (int s4 = 0; s4 < 4; ++s4) { vlo[0][s4] = vtr(vp + (16 * s4) * PV); vhi[0][s4] = vtr(vp + (16 * s4 + 8) * PV); }
;     ...
;     for (int r = 0; r < 16; ++r) { p0[r] = __builtin_amdgcn_exp2f(p0[r]); p1[r] = __builtin_amdgcn_exp2f(p1[r]); sum0 += p0[r]; sum1 += p1[r]; }
;     st.l += sum0 + sum1;
;     bf16x8 pf[4];
;     pf[0] = pack8(p0[0], p0[1], p0[2], p0[3], p0[4], p0[5], p0[6], p0[7]);
;     pf[1] = pack8(p0[8], p0[9], p0[10], p0[11], p0[12], p0[13], p0[14], p0[15]);
;     pf[2] = pack8(p1[0], p1[1], p1[2], p1[3], p1[4], p1[5], p1[6], p1[7]);
;     pf[3] = pack8(p1[8], p1[9], p1[10], p1[11], p1[12], p1[13], p1[14], p1[15]);
;     __builtin_amdgcn_sched_barrier(0);
; #pragma unroll
;     for (int db = 0; db < NDB; ++db) {
;         if (db + 1 < NDB) {
; #pragma unroll
.LBB0_522:
	s_cmp_gt_i32 s59, s7
	s_cbranch_scc1 .LBB0_536
	ds_read_b128 v[180:183], v221 offset:8192
	ds_read_b128 v[160:163], v221 offset:8224
	ds_read_b128 v[176:179], v221 offset:12800
	ds_read_b128 v[164:167], v221 offset:12832
	ds_read_b128 v[156:159], v221 offset:8256
	ds_read_b128 v[152:155], v221 offset:8288
	ds_read_b128 v[172:175], v221 offset:12864
	ds_read_b128 v[168:171], v221 offset:12896
	s_add_i32 s2, s92, s58
	s_add_i32 s2, s2, 63
	s_cmpk_lt_i32 s2, 0xff81
	s_mov_b64 s[2:3], -1
	s_cbranch_scc0 .LBB0_525
	s_waitcnt vmcnt(6) lgkmcnt(7)
	v_mfma_f32_32x32x16_bf16 v[80:95], v[180:183], v[112:115], v[64:79]
	s_mov_b64 s[2:3], 0
	v_exp_f32_e32 v104, v104
	v_exp_f32_e32 v105, v105
	v_add_f32_e32 v184, v104, v184
	v_exp_f32_e32 v106, v106
	v_add_f32_e32 v184, v105, v184
	s_waitcnt vmcnt(5) lgkmcnt(6)
	v_mfma_f32_32x32x16_bf16 v[80:95], v[160:163], v[116:119], v[80:95]
	v_exp_f32_e32 v107, v107
	v_add_f32_e32 v184, v106, v184
	v_exp_f32_e32 v108, v108
	v_add_f32_e32 v184, v107, v184
	v_exp_f32_e32 v109, v109
	s_waitcnt vmcnt(4) lgkmcnt(3)
	v_mfma_f32_32x32x16_bf16 v[80:95], v[156:159], v[120:123], v[80:95]
	v_add_f32_e32 v184, v108, v184
	v_exp_f32_e32 v110, v110
	v_add_f32_e32 v184, v109, v184
	v_exp_f32_e32 v111, v111
	v_add_f32_e32 v184, v110, v184
	s_waitcnt vmcnt(3) lgkmcnt(2)
	v_mfma_f32_32x32x16_bf16 v[80:95], v[152:155], v[124:127], v[80:95]
	v_add_f32_e32 v184, v111, v184
	v_cvt_pk_bf16_f32 v104, v104, v105
	v_cvt_pk_bf16_f32 v105, v106, v107
	v_cvt_pk_bf16_f32 v106, v108, v109
	v_cvt_pk_bf16_f32 v107, v110, v111
	s_nop 1
	v_mfma_f32_32x32x16_bf16 v[48:63], v[104:107], v[226:229], v[48:63]
	v_mfma_f32_32x32x16_bf16 v[32:47], v[104:107], v[230:233], v[32:47]
	v_mfma_f32_32x32x16_bf16 v[16:31], v[104:107], v[234:237], v[16:31]
	v_mfma_f32_32x32x16_bf16 v[0:15], v[104:107], v[238:241], v[0:15]
	v_mfma_f32_32x32x16_bf16 v[96:111], v[176:179], v[112:115], v[64:79]
	v_mfma_f32_32x32x16_bf16 v[96:111], v[164:167], v[116:119], v[96:111]
	ds_read_b64_tr_b16 v[152:153], v217 offset:17408
	ds_read_b64_tr_b16 v[154:155], v217 offset:19968
	ds_read_b64_tr_b16 v[156:157], v217 offset:17472
	ds_read_b64_tr_b16 v[158:159], v217 offset:20032
	ds_read_b64_tr_b16 v[160:161], v217 offset:17536
	ds_read_b64_tr_b16 v[162:163], v217 offset:20096
	ds_read_b64_tr_b16 v[164:165], v217 offset:17600
	ds_read_b64_tr_b16 v[166:167], v217 offset:20160
	s_waitcnt lgkmcnt(9)
	v_mfma_f32_32x32x16_bf16 v[96:111], v[172:175], v[120:123], v[96:111]
	s_waitcnt lgkmcnt(8)
	v_mfma_f32_32x32x16_bf16 v[96:111], v[168:171], v[124:127], v[96:111]
	ds_read_b64_tr_b16 v[226:227], v217 offset:22528
	ds_read_b64_tr_b16 v[228:229], v217 offset:25088
	ds_read_b64_tr_b16 v[230:231], v217 offset:22592
	ds_read_b64_tr_b16 v[232:233], v217 offset:25152
	ds_read_b64_tr_b16 v[234:235], v217 offset:22656
	ds_read_b64_tr_b16 v[236:237], v217 offset:25216
	ds_read_b64_tr_b16 v[238:239], v217 offset:22720
	ds_read_b64_tr_b16 v[240:241], v217 offset:25280
	s_cmp_eq_u32 s58, 0
	s_cselect_b64 s[2:3], -1, 0
	s_cmp_lg_u32 s58, 0
	s_branch .Ldf_max1
; template <int DQK, int DV, bool HAS_BIAS>
; __device__ __forceinline__ void attn_tile(AttnState<DQK, DV>& st, const LAS unsigned char* Kt, const LAS unsigned char* Vt, int bias_mode, const LAS float* tab, int rel0, int nkeys, bool first, LAS float* wsf, int lane) {
;     ...
;     if (HAS_BIAS && bias_mode == 2) {
;         asm volatile("" ::: "memory");
; #pragma unroll
;         for (int r = 0; r < 16; ++r) {
;             const int k = crow(r, hi);
;             const int i0 = min(max(rel0 + k + 128, 0), 191), i1 = min(max(rel0 + k + 160, 0), 191);
;             p0[r] = tab[i0] + st.negm[r]; p1[r] = tab[i1] + st.negm[r];
;         }
;         p0 = __builtin_amdgcn_mfma_f32_32x32x16_bf16(ka[0], st.qf[0], p0, 0, 0, 0);
;         p1 = __builtin_amdgcn_mfma_f32_32x32x16_bf16(kb[0], st.qf[0], p1, 0, 0, 0);
;     } else {
;         p0 = __builtin_amdgcn_mfma_f32_32x32x16_bf16(ka[0], st.qf[0], st.negm, 0, 0, 0);
;         p1 = __builtin_amdgcn_mfma_f32_32x32x16_bf16(kb[0], st.qf[0], st.negm, 0, 0, 0);
;     }
; #pragma unroll
;     for (int ks = 1; ks < KS; ++ks) {
;         p0 = __builtin_amdgcn_mfma_f32_32x32x16_bf16(ka[ks], st.qf[ks], p0, 0, 0, 0);
;         p1 = __builtin_amdgcn_mfma_f32_32x32x16_bf16(kb[ks], st.qf[ks], p1, 0, 0, 0);
;     }
;     const int q4 = (lane & 15) >> 2, blk = (lane >> 4) & 1, pp = lane & 3;
;     const LAS unsigned char* vp = Vt + (4 * hi + q4) * PV + (16 * blk + 4 * pp) * 2;
;     s16x4 vlo[2][4], vhi[2][4];
; #pragma unroll
;     for (int s4 = 0; s4 < 4; ++s4) { vlo[0][s4] = vtr(vp + (16 * s4) * PV); vhi[0][s4] = vtr(vp + (16 * s4 + 8) * PV); }
;     __builtin_amdgcn_sched_barrier(0);
;     if (nkeys < 64) {
; #pragma unroll
;         for (int r = 0; r < 16; ++r) { const int k = crow(r, hi); if (k >= nkeys) p0[r] = -1e30f; if (k + 32 >= nkeys) p1[r] = -1e30f; }
;     }
;     float mxa = __builtin_fmaxf(__builtin_fmaxf(p0[0], p0[1]), p1[0]), mxb = __builtin_fmaxf(__builtin_fmaxf(p0[2], p0[3]), p1[1]);
;     mxa = __builtin_fmaxf(__builtin_fmaxf(mxa, p1[2]), p1[3]);
; #pragma unroll
;     for (int r = 4; r < 16; r += 4) {
;         mxa = __builtin_fmaxf(__builtin_fmaxf(mxa, p0[r]), p0[r + 1]); mxb = __builtin_fmaxf(__builtin_fmaxf(mxb, p0[r + 2]), p0[r + 3]);
;         mxa = __builtin_fmaxf(__builtin_fmaxf(mxa, p1[r]), p1[r + 1]); mxb = __builtin_fmaxf(__builtin_fmaxf(mxb, p1[r + 2]), p1[r + 3]);
;     }
.LBB0_525:
	v_exp_f32_e32 v104, v104
	v_exp_f32_e32 v105, v105
	v_add_f32_e32 v184, v104, v184
	v_exp_f32_e32 v106, v106
	v_add_f32_e32 v184, v105, v184
	v_exp_f32_e32 v107, v107
	v_add_f32_e32 v184, v106, v184
	v_exp_f32_e32 v108, v108
	v_add_f32_e32 v184, v107, v184
	v_exp_f32_e32 v109, v109
	v_add_f32_e32 v184, v108, v184
	v_exp_f32_e32 v110, v110
	v_add_f32_e32 v184, v109, v184
	v_exp_f32_e32 v111, v111
	v_add_f32_e32 v184, v110, v184
	v_add_f32_e32 v184, v111, v184
	v_cvt_pk_bf16_f32 v104, v104, v105
	v_cvt_pk_bf16_f32 v105, v106, v107
	v_cvt_pk_bf16_f32 v106, v108, v109
	v_cvt_pk_bf16_f32 v107, v110, v111
	s_nop 1
	v_mfma_f32_32x32x16_bf16 v[48:63], v[104:107], v[226:229], v[48:63]
	v_mfma_f32_32x32x16_bf16 v[32:47], v[104:107], v[230:233], v[32:47]
	v_mfma_f32_32x32x16_bf16 v[16:31], v[104:107], v[234:237], v[16:31]
	v_mfma_f32_32x32x16_bf16 v[0:15], v[104:107], v[238:241], v[0:15]
	s_nop 6
	v_lshl_add_u32 v224, s58, 2, v225
	ds_read_b32 v80, v224 offset:0
	ds_read_b32 v96, v224 offset:128
	ds_read_b32 v81, v224 offset:4
	ds_read_b32 v97, v224 offset:132
	ds_read_b32 v82, v224 offset:8
	ds_read_b32 v98, v224 offset:136
	ds_read_b32 v83, v224 offset:12
	ds_read_b32 v99, v224 offset:140
	ds_read_b32 v84, v224 offset:32
	ds_read_b32 v100, v224 offset:160
	ds_read_b32 v85, v224 offset:36
	ds_read_b32 v101, v224 offset:164
	ds_read_b32 v86, v224 offset:40
	ds_read_b32 v102, v224 offset:168
	ds_read_b32 v87, v224 offset:44
	ds_read_b32 v103, v224 offset:172
	ds_read_b32 v88, v224 offset:64
	ds_read_b32 v104, v224 offset:192
	ds_read_b32 v89, v224 offset:68
	ds_read_b32 v105, v224 offset:196
	ds_read_b32 v90, v224 offset:72
	ds_read_b32 v106, v224 offset:200
	ds_read_b32 v91, v224 offset:76
	ds_read_b32 v107, v224 offset:204
	ds_read_b32 v92, v224 offset:96
	ds_read_b32 v108, v224 offset:224
	ds_read_b32 v93, v224 offset:100
	ds_read_b32 v109, v224 offset:228
	ds_read_b32 v94, v224 offset:104
	ds_read_b32 v110, v224 offset:232
	ds_read_b32 v95, v224 offset:108
	ds_read_b32 v111, v224 offset:236
	s_waitcnt lgkmcnt(0)
	v_pk_add_f32 v[94:95], v[78:79], v[94:95]
	s_waitcnt lgkmcnt(3)
	v_pk_add_f32 v[92:93], v[76:77], v[92:93]
	v_pk_add_f32 v[90:91], v[74:75], v[90:91]
	v_pk_add_f32 v[88:89], v[72:73], v[88:89]
	v_pk_add_f32 v[86:87], v[70:71], v[86:87]
	v_pk_add_f32 v[84:85], v[68:69], v[84:85]
	v_pk_add_f32 v[82:83], v[66:67], v[82:83]
	v_pk_add_f32 v[80:81], v[64:65], v[80:81]
	s_waitcnt lgkmcnt(1)
	v_pk_add_f32 v[110:111], v[78:79], v[110:111]
	s_waitcnt lgkmcnt(0)
	v_pk_add_f32 v[108:109], v[76:77], v[108:109]
	v_pk_add_f32 v[106:107], v[74:75], v[106:107]
	v_pk_add_f32 v[104:105], v[72:73], v[104:105]
	v_pk_add_f32 v[102:103], v[70:71], v[102:103]
	v_pk_add_f32 v[100:101], v[68:69], v[100:101]
	v_pk_add_f32 v[98:99], v[66:67], v[98:99]
	v_pk_add_f32 v[96:97], v[64:65], v[96:97]
	s_waitcnt vmcnt(6)
	v_mfma_f32_32x32x16_bf16 v[80:95], v[180:183], v[112:115], v[80:95]
	v_mfma_f32_32x32x16_bf16 v[96:111], v[176:179], v[112:115], v[96:111]
.LBB0_527:
	s_waitcnt vmcnt(5) lgkmcnt(6)
	v_mfma_f32_32x32x16_bf16 v[80:95], v[160:163], v[116:119], v[80:95]
	s_cmp_eq_u32 s58, 0
	s_cselect_b64 s[2:3], -1, 0
	s_cmp_lg_u32 s58, 0
	s_waitcnt lgkmcnt(4)
	v_mfma_f32_32x32x16_bf16 v[96:111], v[164:167], v[116:119], v[96:111]
	s_waitcnt vmcnt(4) lgkmcnt(3)
	v_mfma_f32_32x32x16_bf16 v[80:95], v[156:159], v[120:123], v[80:95]
	s_waitcnt lgkmcnt(1)
	v_mfma_f32_32x32x16_bf16 v[96:111], v[172:175], v[120:123], v[96:111]
	s_waitcnt vmcnt(3)
	v_mfma_f32_32x32x16_bf16 v[80:95], v[152:155], v[124:127], v[80:95]
	ds_read_b64_tr_b16 v[152:153], v217 offset:17408
	ds_read_b64_tr_b16 v[154:155], v217 offset:19968
	ds_read_b64_tr_b16 v[156:157], v217 offset:17472
	ds_read_b64_tr_b16 v[158:159], v217 offset:20032
	ds_read_b64_tr_b16 v[160:161], v217 offset:17536
	ds_read_b64_tr_b16 v[162:163], v217 offset:20096
	ds_read_b64_tr_b16 v[164:165], v217 offset:17600
	ds_read_b64_tr_b16 v[166:167], v217 offset:20160
	s_waitcnt lgkmcnt(8)
	v_mfma_f32_32x32x16_bf16 v[96:111], v[168:171], v[124:127], v[96:111]
	ds_read_b64_tr_b16 v[226:227], v217 offset:22528
	ds_read_b64_tr_b16 v[228:229], v217 offset:25088
	ds_read_b64_tr_b16 v[230:231], v217 offset:22592
	ds_read_b64_tr_b16 v[232:233], v217 offset:25152
	ds_read_b64_tr_b16 v[234:235], v217 offset:22656
	ds_read_b64_tr_b16 v[236:237], v217 offset:25216
	ds_read_b64_tr_b16 v[238:239], v217 offset:22720
	ds_read_b64_tr_b16 v[240:241], v217 offset:25280
.Ldf_max1:
	s_nop 1
	v_max_f32_e32 v168, v81, v81
	v_max_f32_e32 v169, v80, v80
	v_max_f32_e32 v168, v169, v168
	s_nop 6
	v_max3_f32 v169, v82, v83, v97
	v_max3_f32 v168, v168, v96, v98
	v_max3_f32 v168, v168, v99, v84
	v_max3_f32 v169, v169, v86, v87
	v_max3_f32 v168, v168, v85, v100
	v_max3_f32 v169, v169, v102, v103
	v_max3_f32 v168, v168, v101, v88
	v_max3_f32 v169, v169, v90, v91
	v_max3_f32 v168, v168, v89, v104
	v_max3_f32 v169, v169, v106, v107
	v_max3_f32 v168, v168, v105, v92
	v_max3_f32 v169, v169, v94, v95
	v_max3_f32 v168, v168, v93, v108
	v_max3_f32 v169, v169, v110, v111
	v_max3_f32 v168, v168, v109, v169
	v_mov_b32_e32 v169, v168
	s_nop 1
	v_permlane32_swap_b32_e32 v168, v169
	v_max_f32_e32 v169, v169, v169
	v_max_f32_e32 v168, v168, v168
	v_max_f32_e32 v168, v168, v169
	s_cbranch_scc0 .LBB0_529
	v_cmp_lt_f32_e32 vcc, s77, v168
	s_cmp_lg_u64 vcc, 0
	s_cselect_b64 s[44:45], -1, 0
	s_cbranch_execz .LBB0_530
	s_branch .LBB0_531

; __device__ __forceinline__ s16x4 vtr(const LAS unsigned char* p) { return __builtin_bit_cast(s16x4, __builtin_amdgcn_ds_read_tr16_b64_v4i16((LAS v4i16_t*)p)); }
; template <int DQK, int DV, bool HAS_BIAS>
; __device__ __forceinline__ void attn_tile(AttnState<DQK, DV>& st, const LAS unsigned char* Kt, const LAS unsigned char* Vt, int bias_mode, const LAS float* tab, int rel0, int nkeys, bool first, LAS float* wsf, int lane) {
;     ...
;     float sum0 = 0.f, sum1 = 0.f;
; #pragma unroll
;     for (int r = 0; r < 16; ++r) { p0[r] = __builtin_amdgcn_exp2f(p0[r]); p1[r] = __builtin_amdgcn_exp2f(p1[r]); sum0 += p0[r]; sum1 += p1[r]; }
;     st.l += sum0 + sum1;
;     bf16x8 pf[4];
;     pf[0] = pack8(p0[0], p0[1], p0[2], p0[3], p0[4], p0[5], p0[6], p0[7]);
;     pf[1] = pack8(p0[8], p0[9], p0[10], p0[11], p0[12], p0[13], p0[14], p0[15]);
;     pf[2] = pack8(p1[0], p1[1], p1[2], p1[3], p1[4], p1[5], p1[6], p1[7]);
;     pf[3] = pack8(p1[8], p1[9], p1[10], p1[11], p1[12], p1[13], p1[14], p1[15]);
;     __builtin_amdgcn_sched_barrier(0);
; #pragma unroll
;     for (int db = 0; db < NDB; ++db) {
;         if (db + 1 < NDB) {
; #pragma unroll
;             for (int s4 = 0; s4 < 4; ++s4) { vlo[(db + 1) & 1][s4] = vtr(vp + (16 * s4) * PV + (db + 1) * 64); vhi[(db + 1) & 1][s4] = vtr(vp + (16 * s4 + 8) * PV + (db + 1) * 64); }
;         }
; #pragma unroll
;         for (int s4 = 0; s4 < 4; ++s4) {
;             const s16x4 lo = vlo[db & 1][s4], h4 = vhi[db & 1][s4];
;             const bf16x8 vb = {lo[0], lo[1], lo[2], lo[3], h4[0], h4[1], h4[2], h4[3]};
;             st.o[db] = __builtin_amdgcn_mfma_f32_32x32x16_bf16(pf[s4], vb, st.o[db], 0, 0, 0);
;         }
;         __builtin_amdgcn_sched_barrier(0);
;     }
.LBB0_535:
	v_exp_f32_e32 v168, v80
	v_exp_f32_e32 v169, v81
	v_add_f32_e32 v222, 0, v168
	v_exp_f32_e32 v170, v82
	v_add_f32_e32 v222, v169, v222
	v_exp_f32_e32 v171, v83
	v_add_f32_e32 v222, v170, v222
	v_exp_f32_e32 v172, v84
	v_add_f32_e32 v222, v171, v222
	v_exp_f32_e32 v173, v85
	v_add_f32_e32 v222, v172, v222
	v_exp_f32_e32 v174, v86
	v_add_f32_e32 v222, v173, v222
	v_exp_f32_e32 v175, v87
	v_add_f32_e32 v222, v174, v222
	v_cvt_pk_bf16_f32 v80, v168, v169
	v_add_f32_e32 v222, v175, v222
	v_cvt_pk_bf16_f32 v81, v170, v171
	v_cvt_pk_bf16_f32 v82, v172, v173
	v_cvt_pk_bf16_f32 v83, v174, v175
	s_nop 1
	s_waitcnt lgkmcnt(8)
	v_mfma_f32_32x32x16_bf16 v[48:63], v[80:83], v[152:155], v[48:63]
	v_exp_f32_e32 v176, v88
	v_exp_f32_e32 v177, v89
	v_add_f32_e32 v222, v176, v222
	v_exp_f32_e32 v178, v90
	v_add_f32_e32 v222, v177, v222
	v_mfma_f32_32x32x16_bf16 v[32:47], v[80:83], v[156:159], v[32:47]
	v_exp_f32_e32 v179, v91
	v_add_f32_e32 v222, v178, v222
	v_exp_f32_e32 v180, v92
	v_add_f32_e32 v222, v179, v222
	v_exp_f32_e32 v181, v93
	v_mfma_f32_32x32x16_bf16 v[16:31], v[80:83], v[160:163], v[16:31]
	v_add_f32_e32 v222, v180, v222
	v_exp_f32_e32 v182, v94
	v_add_f32_e32 v222, v181, v222
	v_exp_f32_e32 v183, v95
	v_add_f32_e32 v222, v182, v222
	v_mfma_f32_32x32x16_bf16 v[0:15], v[80:83], v[164:167], v[0:15]
	v_cvt_pk_bf16_f32 v84, v176, v177
	v_add_f32_e32 v222, v183, v222
	v_cvt_pk_bf16_f32 v85, v178, v179
	v_cvt_pk_bf16_f32 v86, v180, v181
	v_cvt_pk_bf16_f32 v87, v182, v183
	ds_read_b64_tr_b16 v[152:153], v217 offset:27648
	ds_read_b64_tr_b16 v[154:155], v217 offset:30208
	ds_read_b64_tr_b16 v[156:157], v217 offset:27712
	ds_read_b64_tr_b16 v[158:159], v217 offset:30272
	ds_read_b64_tr_b16 v[160:161], v217 offset:27776
	ds_read_b64_tr_b16 v[162:163], v217 offset:30336
	ds_read_b64_tr_b16 v[164:165], v217 offset:27840
	ds_read_b64_tr_b16 v[166:167], v217 offset:30400
	s_waitcnt lgkmcnt(8)
	v_mfma_f32_32x32x16_bf16 v[48:63], v[84:87], v[226:229], v[48:63]
	v_exp_f32_e32 v168, v96
	v_exp_f32_e32 v169, v97
	v_add_f32_e32 v223, 0, v168
	v_exp_f32_e32 v170, v98
	v_add_f32_e32 v223, v169, v223
	v_mfma_f32_32x32x16_bf16 v[32:47], v[84:87], v[230:233], v[32:47]
	v_exp_f32_e32 v171, v99
	v_add_f32_e32 v223, v170, v223
	v_exp_f32_e32 v172, v100
	v_add_f32_e32 v223, v171, v223
	v_exp_f32_e32 v173, v101
	v_mfma_f32_32x32x16_bf16 v[16:31], v[84:87], v[234:237], v[16:31]
	v_add_f32_e32 v223, v172, v223
	v_exp_f32_e32 v174, v102
	v_add_f32_e32 v223, v173, v223
	v_exp_f32_e32 v175, v103
	v_add_f32_e32 v223, v174, v223
	v_mfma_f32_32x32x16_bf16 v[0:15], v[84:87], v[238:241], v[0:15]
	v_cvt_pk_bf16_f32 v88, v168, v169
	v_add_f32_e32 v223, v175, v223
	v_cvt_pk_bf16_f32 v89, v170, v171
	v_cvt_pk_bf16_f32 v90, v172, v173
	v_cvt_pk_bf16_f32 v91, v174, v175
	ds_read_b64_tr_b16 v[226:227], v217 offset:32768
	ds_read_b64_tr_b16 v[228:229], v217 offset:35328
	ds_read_b64_tr_b16 v[230:231], v217 offset:32832
	ds_read_b64_tr_b16 v[232:233], v217 offset:35392
	ds_read_b64_tr_b16 v[234:235], v217 offset:32896
	ds_read_b64_tr_b16 v[236:237], v217 offset:35456
	ds_read_b64_tr_b16 v[238:239], v217 offset:32960
	ds_read_b64_tr_b16 v[240:241], v217 offset:35520
	s_waitcnt lgkmcnt(8)
	v_mfma_f32_32x32x16_bf16 v[48:63], v[88:91], v[152:155], v[48:63]
	v_add_f32_e32 v222, v223, v222
	v_mfma_f32_32x32x16_bf16 v[32:47], v[88:91], v[156:159], v[32:47]
	v_add_f32_e32 v184, v184, v222
	v_mfma_f32_32x32x16_bf16 v[16:31], v[88:91], v[160:163], v[16:31]
	v_mfma_f32_32x32x16_bf16 v[0:15], v[88:91], v[164:167], v[0:15]

; #define LAS __attribute__((address_space(3)))
; __device__ __forceinline__ int crow(int r, int hi) { return (r & 3) + 8 * (r >> 2) + 4 * hi; }
; template <int DQK, int DV, bool HAS_BIAS>
; __device__ __forceinline__ void attn_tile(AttnState<DQK, DV>& st, const LAS unsigned char* Kt, const LAS unsigned char* Vt, int bias_mode, const LAS float* tab, int rel0, int nkeys, bool first, LAS float* wsf, int lane) {
;     ...
;     if (HAS_BIAS && bias_mode == 2) {
;         asm volatile("" ::: "memory");
; #pragma unroll
;         for (int r = 0; r < 16; ++r) {
;             const int k = crow(r, hi);
;             const int i0 = min(max(rel0 + k + 128, 0), 191), i1 = min(max(rel0 + k + 160, 0), 191);
;             p0[r] = tab[i0] + st.negm[r]; p1[r] = tab[i1] + st.negm[r];
;         }
;         p0 = __builtin_amdgcn_mfma_f32_32x32x16_bf16(ka[0], st.qf[0], p0, 0, 0, 0);
;         p1 = __builtin_amdgcn_mfma_f32_32x32x16_bf16(kb[0], st.qf[0], p1, 0, 0, 0);
;     } else {
;         p0 = __builtin_amdgcn_mfma_f32_32x32x16_bf16(ka[0], st.qf[0], st.negm, 0, 0, 0);
;         p1 = __builtin_amdgcn_mfma_f32_32x32x16_bf16(kb[0], st.qf[0], st.negm, 0, 0, 0);
;     }
; #pragma unroll
;     for (int ks = 1; ks < KS; ++ks) {
;         p0 = __builtin_amdgcn_mfma_f32_32x32x16_bf16(ka[ks], st.qf[ks], p0, 0, 0, 0);
;         p1 = __builtin_amdgcn_mfma_f32_32x32x16_bf16(kb[ks], st.qf[ks], p1, 0, 0, 0);
;     }
;     const int q4 = (lane & 15) >> 2, blk = (lane >> 4) & 1, pp = lane & 3;
;     const LAS unsigned char* vp = Vt + (4 * hi + q4) * PV + (16 * blk + 4 * pp) * 2;
;     s16x4 vlo[2][4], vhi[2][4];
; #pragma unroll
;     for (int s4 = 0; s4 < 4; ++s4) { vlo[0][s4] = vtr(vp + (16 * s4) * PV); vhi[0][s4] = vtr(vp + (16 * s4 + 8) * PV); }
;     ...
;     for (int r = 0; r < 16; ++r) { p0[r] = __builtin_amdgcn_exp2f(p0[r]); p1[r] = __builtin_amdgcn_exp2f(p1[r]); sum0 += p0[r]; sum1 += p1[r]; }
;     st.l += sum0 + sum1;
;     bf16x8 pf[4];
;     pf[0] = pack8(p0[0], p0[1], p0[2], p0[3], p0[4], p0[5], p0[6], p0[7]);
;     pf[1] = pack8(p0[8], p0[9], p0[10], p0[11], p0[12], p0[13], p0[14], p0[15]);
;     pf[2] = pack8(p1[0], p1[1], p1[2], p1[3], p1[4], p1[5], p1[6], p1[7]);
;     pf[3] = pack8(p1[8], p1[9], p1[10], p1[11], p1[12], p1[13], p1[14], p1[15]);
;     __builtin_amdgcn_sched_barrier(0);
; #pragma unroll
;     for (int db = 0; db < NDB; ++db) {
;         if (db + 1 < NDB) {
; #pragma unroll
.LBB0_543:
	ds_read_b128 v[180:183], v221 offset:37888
	ds_read_b128 v[160:163], v221 offset:37920
	ds_read_b128 v[176:179], v221 offset:42496
	ds_read_b128 v[164:167], v221 offset:42528
	ds_read_b128 v[156:159], v221 offset:37952
	ds_read_b128 v[152:155], v221 offset:37984
	ds_read_b128 v[172:175], v221 offset:42560
	ds_read_b128 v[168:171], v221 offset:42592
	s_add_i32 s2, s92, s58
	s_addk_i32 s2, 0x7f
	s_cmpk_lt_i32 s2, 0xff81
	s_mov_b64 s[2:3], -1
	s_cbranch_scc0 .LBB0_545
	s_waitcnt lgkmcnt(7)
	v_mfma_f32_32x32x16_bf16 v[80:95], v[180:183], v[112:115], v[64:79]
	s_mov_b64 s[2:3], 0
	v_exp_f32_e32 v104, v104
	v_exp_f32_e32 v105, v105
	v_add_f32_e32 v184, v104, v184
	v_exp_f32_e32 v106, v106
	v_add_f32_e32 v184, v105, v184
	s_waitcnt lgkmcnt(6)
	v_mfma_f32_32x32x16_bf16 v[80:95], v[160:163], v[116:119], v[80:95]
	v_exp_f32_e32 v107, v107
	v_add_f32_e32 v184, v106, v184
	v_exp_f32_e32 v108, v108
	v_add_f32_e32 v184, v107, v184
	v_exp_f32_e32 v109, v109
	s_waitcnt lgkmcnt(3)
	v_mfma_f32_32x32x16_bf16 v[80:95], v[156:159], v[120:123], v[80:95]
	v_add_f32_e32 v184, v108, v184
	v_exp_f32_e32 v110, v110
	v_add_f32_e32 v184, v109, v184
	v_exp_f32_e32 v111, v111
	v_add_f32_e32 v184, v110, v184
	s_waitcnt lgkmcnt(2)
	v_mfma_f32_32x32x16_bf16 v[80:95], v[152:155], v[124:127], v[80:95]
	v_add_f32_e32 v184, v111, v184
	v_cvt_pk_bf16_f32 v104, v104, v105
	v_cvt_pk_bf16_f32 v105, v106, v107
	v_cvt_pk_bf16_f32 v106, v108, v109
	v_cvt_pk_bf16_f32 v107, v110, v111
	s_nop 1
	v_mfma_f32_32x32x16_bf16 v[48:63], v[104:107], v[226:229], v[48:63]
	v_mfma_f32_32x32x16_bf16 v[32:47], v[104:107], v[230:233], v[32:47]
	v_mfma_f32_32x32x16_bf16 v[16:31], v[104:107], v[234:237], v[16:31]
	v_mfma_f32_32x32x16_bf16 v[0:15], v[104:107], v[238:241], v[0:15]
	v_mfma_f32_32x32x16_bf16 v[96:111], v[176:179], v[112:115], v[64:79]
	v_mfma_f32_32x32x16_bf16 v[96:111], v[164:167], v[116:119], v[96:111]
	ds_read_b64_tr_b16 v[152:153], v217 offset:47104
	ds_read_b64_tr_b16 v[154:155], v217 offset:49664
	ds_read_b64_tr_b16 v[156:157], v217 offset:47168
	ds_read_b64_tr_b16 v[158:159], v217 offset:49728
	ds_read_b64_tr_b16 v[160:161], v217 offset:47232
	ds_read_b64_tr_b16 v[162:163], v217 offset:49792
	ds_read_b64_tr_b16 v[164:165], v217 offset:47296
	ds_read_b64_tr_b16 v[166:167], v217 offset:49856
	s_waitcnt lgkmcnt(9)
	v_mfma_f32_32x32x16_bf16 v[96:111], v[172:175], v[120:123], v[96:111]
	s_waitcnt lgkmcnt(8)
	v_mfma_f32_32x32x16_bf16 v[96:111], v[168:171], v[124:127], v[96:111]
	ds_read_b64_tr_b16 v[226:227], v217 offset:52224
	ds_read_b64_tr_b16 v[228:229], v217 offset:54784
	ds_read_b64_tr_b16 v[230:231], v217 offset:52288
	ds_read_b64_tr_b16 v[232:233], v217 offset:54848
	ds_read_b64_tr_b16 v[234:235], v217 offset:52352
	ds_read_b64_tr_b16 v[236:237], v217 offset:54912
	ds_read_b64_tr_b16 v[238:239], v217 offset:52416
	ds_read_b64_tr_b16 v[240:241], v217 offset:54976
	s_branch .Ldf_max2
.LBB0_545:
	v_exp_f32_e32 v104, v104
	v_exp_f32_e32 v105, v105
	v_add_f32_e32 v184, v104, v184
	v_exp_f32_e32 v106, v106
	v_add_f32_e32 v184, v105, v184
	v_exp_f32_e32 v107, v107
	v_add_f32_e32 v184, v106, v184
	v_exp_f32_e32 v108, v108
	v_add_f32_e32 v184, v107, v184
	v_exp_f32_e32 v109, v109
	v_add_f32_e32 v184, v108, v184
	v_exp_f32_e32 v110, v110
	v_add_f32_e32 v184, v109, v184
	v_exp_f32_e32 v111, v111
	v_add_f32_e32 v184, v110, v184
	v_add_f32_e32 v184, v111, v184
	v_cvt_pk_bf16_f32 v104, v104, v105
	v_cvt_pk_bf16_f32 v105, v106, v107
	v_cvt_pk_bf16_f32 v106, v108, v109
	v_cvt_pk_bf16_f32 v107, v110, v111
	s_nop 1
	v_mfma_f32_32x32x16_bf16 v[48:63], v[104:107], v[226:229], v[48:63]
	v_mfma_f32_32x32x16_bf16 v[32:47], v[104:107], v[230:233], v[32:47]
	v_mfma_f32_32x32x16_bf16 v[16:31], v[104:107], v[234:237], v[16:31]
	v_mfma_f32_32x32x16_bf16 v[0:15], v[104:107], v[238:241], v[0:15]
	s_nop 6
	v_lshl_add_u32 v224, s58, 2, v225
	ds_read_b32 v80, v224 offset:256
	ds_read_b32 v96, v224 offset:384
	ds_read_b32 v81, v224 offset:260
	ds_read_b32 v97, v224 offset:388
	ds_read_b32 v82, v224 offset:264
	ds_read_b32 v98, v224 offset:392
	ds_read_b32 v83, v224 offset:268
	ds_read_b32 v99, v224 offset:396
	ds_read_b32 v84, v224 offset:288
	ds_read_b32 v100, v224 offset:416
	ds_read_b32 v85, v224 offset:292
	ds_read_b32 v101, v224 offset:420
	ds_read_b32 v86, v224 offset:296
	ds_read_b32 v102, v224 offset:424
	ds_read_b32 v87, v224 offset:300
	ds_read_b32 v103, v224 offset:428
	ds_read_b32 v88, v224 offset:320
	ds_read_b32 v104, v224 offset:448
	ds_read_b32 v89, v224 offset:324
	ds_read_b32 v105, v224 offset:452
	ds_read_b32 v90, v224 offset:328
	ds_read_b32 v106, v224 offset:456
	ds_read_b32 v91, v224 offset:332
	ds_read_b32 v107, v224 offset:460
	ds_read_b32 v92, v224 offset:352
	ds_read_b32 v108, v224 offset:480
	ds_read_b32 v93, v224 offset:356
	ds_read_b32 v109, v224 offset:484
	ds_read_b32 v94, v224 offset:360
	ds_read_b32 v110, v224 offset:488
	ds_read_b32 v95, v224 offset:364
	ds_read_b32 v111, v224 offset:492
	s_waitcnt lgkmcnt(0)
	v_pk_add_f32 v[94:95], v[78:79], v[94:95]
	s_waitcnt lgkmcnt(3)
	v_pk_add_f32 v[92:93], v[76:77], v[92:93]
	v_pk_add_f32 v[90:91], v[74:75], v[90:91]
	v_pk_add_f32 v[88:89], v[72:73], v[88:89]
	v_pk_add_f32 v[86:87], v[70:71], v[86:87]
	v_pk_add_f32 v[84:85], v[68:69], v[84:85]
	v_pk_add_f32 v[82:83], v[66:67], v[82:83]
	v_pk_add_f32 v[80:81], v[64:65], v[80:81]
	s_waitcnt lgkmcnt(1)
	v_pk_add_f32 v[110:111], v[78:79], v[110:111]
	s_waitcnt lgkmcnt(0)
	v_pk_add_f32 v[108:109], v[76:77], v[108:109]
	v_pk_add_f32 v[106:107], v[74:75], v[106:107]
	v_pk_add_f32 v[104:105], v[72:73], v[104:105]
	v_pk_add_f32 v[102:103], v[70:71], v[102:103]
	v_pk_add_f32 v[100:101], v[68:69], v[100:101]
	v_pk_add_f32 v[98:99], v[66:67], v[98:99]
	v_pk_add_f32 v[96:97], v[64:65], v[96:97]
	v_mfma_f32_32x32x16_bf16 v[80:95], v[180:183], v[112:115], v[80:95]
	s_nop 0
	v_mfma_f32_32x32x16_bf16 v[96:111], v[176:179], v[112:115], v[96:111]

; __device__ __forceinline__ int crow(int r, int hi) { return (r & 3) + 8 * (r >> 2) + 4 * hi; }
; __device__ __forceinline__ float xmax32(float v) { auto rr = __builtin_amdgcn_permlane32_swap(__float_as_uint(v), __float_as_uint(v), false, false); return fmaxf(__uint_as_float(rr[0]), __uint_as_float(rr[1])); }
; template <int DQK, int DV, bool HAS_BIAS>
; __device__ __forceinline__ void attn_tile(AttnState<DQK, DV>& st, const LAS unsigned char* Kt, const LAS unsigned char* Vt, int bias_mode, const LAS float* tab, int rel0, int nkeys, bool first, LAS float* wsf, int lane) {
;     ...
;     float mxa = __builtin_fmaxf(__builtin_fmaxf(p0[0], p0[1]), p1[0]), mxb = __builtin_fmaxf(__builtin_fmaxf(p0[2], p0[3]), p1[1]);
;     mxa = __builtin_fmaxf(__builtin_fmaxf(mxa, p1[2]), p1[3]);
; #pragma unroll
;     for (int r = 4; r < 16; r += 4) {
;         mxa = __builtin_fmaxf(__builtin_fmaxf(mxa, p0[r]), p0[r + 1]); mxb = __builtin_fmaxf(__builtin_fmaxf(mxb, p0[r + 2]), p0[r + 3]);
;         mxa = __builtin_fmaxf(__builtin_fmaxf(mxa, p1[r]), p1[r + 1]); mxb = __builtin_fmaxf(__builtin_fmaxf(mxb, p1[r + 2]), p1[r + 3]);
;     }
;     const float mx = xmax32(__builtin_fmaxf(mxa, mxb));
;     if (first || __any(mx > ATT_THR)) {
;         const float dl = first ? mx : __builtin_fmaxf(mx, 0.f);
;         st.m += dl;
; #pragma unroll
;         for (int r = 0; r < 16; ++r) { st.negm[r] = -st.m; p0[r] -= dl; p1[r] -= dl; }
;         const float f = __builtin_amdgcn_exp2f(-dl);
;         st.l *= f;
;         if (hi == 0) wsf[q] = f;
; #pragma unroll
;         for (int r = 0; r < 16; ++r) { const float fr = wsf[crow(r, hi)];
; #pragma unroll
;             for (int db = 0; db < NDB; ++db) st.o[db][r] *= fr; }
;     }
.Ldf_max2:
	s_nop 1
	v_max_f32_e32 v168, v81, v81
	v_max_f32_e32 v169, v80, v80
	v_max_f32_e32 v168, v169, v168
	s_nop 6
	v_max3_f32 v169, v82, v83, v97
	v_max3_f32 v168, v168, v96, v98
	v_max3_f32 v168, v168, v99, v84
	v_max3_f32 v169, v169, v86, v87
	v_max3_f32 v168, v168, v85, v100
	v_max3_f32 v169, v169, v102, v103
	v_max3_f32 v168, v168, v101, v88
	v_max3_f32 v169, v169, v90, v91
	v_max3_f32 v168, v168, v89, v104
	v_max3_f32 v169, v169, v106, v107
	v_max3_f32 v168, v168, v105, v92
	v_max3_f32 v169, v169, v94, v95
	v_max3_f32 v168, v168, v93, v108
	v_max3_f32 v169, v169, v110, v111
	v_max3_f32 v168, v168, v109, v169
	v_mov_b32_e32 v169, v168
	s_nop 1
	v_permlane32_swap_b32_e32 v168, v169
	v_max_f32_e32 v169, v169, v169
	v_max_f32_e32 v168, v168, v168
	v_max_f32_e32 v168, v168, v169
	v_cmp_lt_f32_e32 vcc, s77, v168
	s_cbranch_vccz .LBB0_551
	v_max_f32_e32 v64, v168, v168
	v_max_f32_e32 v168, 0, v64
	v_exp_f32_e64 v169, -v168
	s_and_saveexec_b64 s[2:3], s[0:1]
	ds_write_b32 v216, v169 offset:6144
	s_or_b64 exec, exec, s[2:3]
	v_add_f32_e32 v220, v220, v168
	v_pk_add_f32 v[80:81], v[80:81], v[168:169] op_sel_hi:[1,0] neg_lo:[0,1] neg_hi:[0,1]
	v_pk_add_f32 v[96:97], v[96:97], v[168:169] op_sel_hi:[1,0] neg_lo:[0,1] neg_hi:[0,1]
	v_pk_add_f32 v[82:83], v[82:83], v[168:169] op_sel_hi:[1,0] neg_lo:[0,1] neg_hi:[0,1]
	v_pk_add_f32 v[98:99], v[98:99], v[168:169] op_sel_hi:[1,0] neg_lo:[0,1] neg_hi:[0,1]
	v_pk_add_f32 v[84:85], v[84:85], v[168:169] op_sel_hi:[1,0] neg_lo:[0,1] neg_hi:[0,1]
	v_pk_add_f32 v[100:101], v[100:101], v[168:169] op_sel_hi:[1,0] neg_lo:[0,1] neg_hi:[0,1]
	v_pk_add_f32 v[86:87], v[86:87], v[168:169] op_sel_hi:[1,0] neg_lo:[0,1] neg_hi:[0,1]
	v_pk_add_f32 v[102:103], v[102:103], v[168:169] op_sel_hi:[1,0] neg_lo:[0,1] neg_hi:[0,1]
	v_pk_add_f32 v[88:89], v[88:89], v[168:169] op_sel_hi:[1,0] neg_lo:[0,1] neg_hi:[0,1]
	v_pk_add_f32 v[104:105], v[104:105], v[168:169] op_sel_hi:[1,0] neg_lo:[0,1] neg_hi:[0,1]
	v_pk_add_f32 v[90:91], v[90:91], v[168:169] op_sel_hi:[1,0] neg_lo:[0,1] neg_hi:[0,1]
	v_pk_add_f32 v[106:107], v[106:107], v[168:169] op_sel_hi:[1,0] neg_lo:[0,1] neg_hi:[0,1]
	v_pk_add_f32 v[92:93], v[92:93], v[168:169] op_sel_hi:[1,0] neg_lo:[0,1] neg_hi:[0,1]
	v_pk_add_f32 v[108:109], v[108:109], v[168:169] op_sel_hi:[1,0] neg_lo:[0,1] neg_hi:[0,1]
	v_pk_add_f32 v[94:95], v[94:95], v[168:169] op_sel_hi:[1,0] neg_lo:[0,1] neg_hi:[0,1]
	v_pk_add_f32 v[110:111], v[110:111], v[168:169] op_sel_hi:[1,0] neg_lo:[0,1] neg_hi:[0,1]
	v_mul_f32_e32 v184, v184, v169
	ds_read_b128 v[168:171], v213 offset:6144
	ds_read_b128 v[172:175], v213 offset:6176
	ds_read_b128 v[176:179], v213 offset:6208
	ds_read_b128 v[180:183], v213 offset:6240
	v_xor_b32_e32 v64, 0x80000000, v220
	v_mov_b32_e32 v65, v64
	v_mov_b32_e32 v66, v64
	v_mov_b32_e32 v67, v64
	v_mov_b32_e32 v68, v64
	v_mov_b32_e32 v69, v64
	v_mov_b32_e32 v70, v64
	v_mov_b32_e32 v71, v64
	v_mov_b32_e32 v72, v64
	v_mov_b32_e32 v73, v64
	v_mov_b32_e32 v74, v64
	v_mov_b32_e32 v75, v64
	v_mov_b32_e32 v76, v64
	v_mov_b32_e32 v77, v64
	v_mov_b32_e32 v78, v64
	v_mov_b32_e32 v79, v64
	s_waitcnt lgkmcnt(0)
	v_pk_mul_f32 v[62:63], v[62:63], v[182:183]
	v_pk_mul_f32 v[58:59], v[58:59], v[178:179]
	v_pk_mul_f32 v[54:55], v[54:55], v[174:175]
	v_pk_mul_f32 v[50:51], v[50:51], v[170:171]
	v_pk_mul_f32 v[60:61], v[60:61], v[180:181]
	v_pk_mul_f32 v[56:57], v[56:57], v[176:177]
	v_pk_mul_f32 v[52:53], v[52:53], v[172:173]
	v_pk_mul_f32 v[48:49], v[48:49], v[168:169]
	v_pk_mul_f32 v[46:47], v[46:47], v[182:183]
	v_pk_mul_f32 v[42:43], v[42:43], v[178:179]
	v_pk_mul_f32 v[38:39], v[38:39], v[174:175]
	v_pk_mul_f32 v[34:35], v[34:35], v[170:171]
	v_pk_mul_f32 v[44:45], v[44:45], v[180:181]
	v_pk_mul_f32 v[40:41], v[40:41], v[176:177]
	v_pk_mul_f32 v[36:37], v[36:37], v[172:173]
	v_pk_mul_f32 v[32:33], v[32:33], v[168:169]
	v_pk_mul_f32 v[30:31], v[30:31], v[182:183]
	v_pk_mul_f32 v[26:27], v[26:27], v[178:179]
	v_pk_mul_f32 v[22:23], v[22:23], v[174:175]
	v_pk_mul_f32 v[18:19], v[18:19], v[170:171]
	v_pk_mul_f32 v[28:29], v[28:29], v[180:181]
	v_pk_mul_f32 v[24:25], v[24:25], v[176:177]
	v_pk_mul_f32 v[20:21], v[20:21], v[172:173]
	v_pk_mul_f32 v[16:17], v[16:17], v[168:169]
	v_pk_mul_f32 v[14:15], v[14:15], v[182:183]
	v_pk_mul_f32 v[10:11], v[10:11], v[178:179]
	v_pk_mul_f32 v[6:7], v[6:7], v[174:175]
	v_pk_mul_f32 v[2:3], v[2:3], v[170:171]
	v_pk_mul_f32 v[12:13], v[12:13], v[180:181]
	v_pk_mul_f32 v[8:9], v[8:9], v[176:177]
	v_pk_mul_f32 v[4:5], v[4:5], v[172:173]
	v_pk_mul_f32 v[0:1], v[0:1], v[168:169]
; __device__ __forceinline__ float xsum32(float v) { auto rr = __builtin_amdgcn_permlane32_swap(__float_as_uint(v), __float_as_uint(v), false, false); return __uint_as_float(rr[0]) + __uint_as_float(rr[1]); }
; __device__ __forceinline__ s16x4 vtr(const LAS unsigned char* p) { return __builtin_bit_cast(s16x4, __builtin_amdgcn_ds_read_tr16_b64_v4i16((LAS v4i16_t*)p)); }
; template <int DQK, int DV, bool HAS_BIAS>
; __device__ __forceinline__ void attn_tile(AttnState<DQK, DV>& st, const LAS unsigned char* Kt, const LAS unsigned char* Vt, int bias_mode, const LAS float* tab, int rel0, int nkeys, bool first, LAS float* wsf, int lane) {
;     ...
;     float sum0 = 0.f, sum1 = 0.f;
; #pragma unroll
;     for (int r = 0; r < 16; ++r) { p0[r] = __builtin_amdgcn_exp2f(p0[r]); p1[r] = __builtin_amdgcn_exp2f(p1[r]); sum0 += p0[r]; sum1 += p1[r]; }
;     st.l += sum0 + sum1;
;     bf16x8 pf[4];
;     pf[0] = pack8(p0[0], p0[1], p0[2], p0[3], p0[4], p0[5], p0[6], p0[7]);
;     pf[1] = pack8(p0[8], p0[9], p0[10], p0[11], p0[12], p0[13], p0[14], p0[15]);
;     pf[2] = pack8(p1[0], p1[1], p1[2], p1[3], p1[4], p1[5], p1[6], p1[7]);
;     pf[3] = pack8(p1[8], p1[9], p1[10], p1[11], p1[12], p1[13], p1[14], p1[15]);
;     __builtin_amdgcn_sched_barrier(0);
; #pragma unroll
;     for (int db = 0; db < NDB; ++db) {
;         if (db + 1 < NDB) {
; #pragma unroll
;             for (int s4 = 0; s4 < 4; ++s4) { vlo[(db + 1) & 1][s4] = vtr(vp + (16 * s4) * PV + (db + 1) * 64); vhi[(db + 1) & 1][s4] = vtr(vp + (16 * s4 + 8) * PV + (db + 1) * 64); }
;         }
; #pragma unroll
;         for (int s4 = 0; s4 < 4; ++s4) {
;             const s16x4 lo = vlo[db & 1][s4], h4 = vhi[db & 1][s4];
;             const bf16x8 vb = {lo[0], lo[1], lo[2], lo[3], h4[0], h4[1], h4[2], h4[3]};
;             st.o[db] = __builtin_amdgcn_mfma_f32_32x32x16_bf16(pf[s4], vb, st.o[db], 0, 0, 0);
;         }
;         __builtin_amdgcn_sched_barrier(0);
;     }
; template <bool DIFF>
; __device__ __forceinline__ void attn_unit_coop(const Grp& G, int b, int h, int qb, int n, LAS unsigned char* lds, const int tid_in) {
;     ...
;         const float lt = xsum32(st.l);
;         if (hi == 0) wsf[32 + q] = lt;
.LBB0_551:
	v_exp_f32_e32 v168, v80
	v_exp_f32_e32 v169, v81
	v_add_f32_e32 v200, 0, v168
	v_exp_f32_e32 v170, v82
	v_add_f32_e32 v200, v169, v200
	v_exp_f32_e32 v171, v83
	v_add_f32_e32 v200, v170, v200
	v_exp_f32_e32 v172, v84
	v_add_f32_e32 v200, v171, v200
	v_exp_f32_e32 v173, v85
	v_add_f32_e32 v200, v172, v200
	v_exp_f32_e32 v174, v86
	v_add_f32_e32 v200, v173, v200
	v_exp_f32_e32 v175, v87
	v_add_f32_e32 v200, v174, v200
	v_cvt_pk_bf16_f32 v80, v168, v169
	v_add_f32_e32 v200, v175, v200
	v_cvt_pk_bf16_f32 v81, v170, v171
	v_cvt_pk_bf16_f32 v82, v172, v173
	v_cvt_pk_bf16_f32 v83, v174, v175
	s_nop 1
	s_waitcnt lgkmcnt(8)
	v_mfma_f32_32x32x16_bf16 v[48:63], v[80:83], v[152:155], v[48:63]
	v_exp_f32_e32 v176, v88
	v_exp_f32_e32 v177, v89
	v_add_f32_e32 v200, v176, v200
	v_exp_f32_e32 v178, v90
	v_add_f32_e32 v200, v177, v200
	v_mfma_f32_32x32x16_bf16 v[32:47], v[80:83], v[156:159], v[32:47]
	v_exp_f32_e32 v179, v91
	v_add_f32_e32 v200, v178, v200
	v_exp_f32_e32 v180, v92
	v_add_f32_e32 v200, v179, v200
	v_exp_f32_e32 v181, v93
	v_mfma_f32_32x32x16_bf16 v[16:31], v[80:83], v[160:163], v[16:31]
	v_add_f32_e32 v200, v180, v200
	v_exp_f32_e32 v182, v94
	v_add_f32_e32 v200, v181, v200
	v_exp_f32_e32 v183, v95
	v_add_f32_e32 v200, v182, v200
	v_mfma_f32_32x32x16_bf16 v[0:15], v[80:83], v[164:167], v[0:15]
	v_cvt_pk_bf16_f32 v84, v176, v177
	v_add_f32_e32 v200, v183, v200
	v_cvt_pk_bf16_f32 v85, v178, v179
	v_cvt_pk_bf16_f32 v86, v180, v181
	v_cvt_pk_bf16_f32 v87, v182, v183
	ds_read_b64_tr_b16 v[152:153], v217 offset:57344
	ds_read_b64_tr_b16 v[154:155], v217 offset:59904
	ds_read_b64_tr_b16 v[156:157], v217 offset:57408
	ds_read_b64_tr_b16 v[158:159], v217 offset:59968
	ds_read_b64_tr_b16 v[160:161], v217 offset:57472
	ds_read_b64_tr_b16 v[162:163], v217 offset:60032
	ds_read_b64_tr_b16 v[164:165], v217 offset:57536
	ds_read_b64_tr_b16 v[166:167], v217 offset:60096
	s_waitcnt lgkmcnt(8)
	v_mfma_f32_32x32x16_bf16 v[48:63], v[84:87], v[226:229], v[48:63]
	v_exp_f32_e32 v168, v96
	v_exp_f32_e32 v169, v97
	v_add_f32_e32 v201, 0, v168
	v_exp_f32_e32 v170, v98
	v_add_f32_e32 v201, v169, v201
	v_mfma_f32_32x32x16_bf16 v[32:47], v[84:87], v[230:233], v[32:47]
	v_exp_f32_e32 v171, v99
	v_add_f32_e32 v201, v170, v201
	v_exp_f32_e32 v172, v100
	v_add_f32_e32 v201, v171, v201
	v_exp_f32_e32 v173, v101
	v_mfma_f32_32x32x16_bf16 v[16:31], v[84:87], v[234:237], v[16:31]
	v_add_f32_e32 v201, v172, v201
	v_exp_f32_e32 v174, v102
	v_add_f32_e32 v201, v173, v201
	v_exp_f32_e32 v175, v103
	v_add_f32_e32 v201, v174, v201
	v_mfma_f32_32x32x16_bf16 v[0:15], v[84:87], v[238:241], v[0:15]
	v_cvt_pk_bf16_f32 v88, v168, v169
	v_add_f32_e32 v201, v175, v201
	v_cvt_pk_bf16_f32 v89, v170, v171
	v_cvt_pk_bf16_f32 v90, v172, v173
	v_cvt_pk_bf16_f32 v91, v174, v175
	ds_read_b64_tr_b16 v[226:227], v217 offset:62464
	ds_read_b64_tr_b16 v[228:229], v217 offset:65024
	ds_read_b64_tr_b16 v[230:231], v217 offset:62528
	ds_read_b64_tr_b16 v[232:233], v217 offset:65088
	ds_read_b64_tr_b16 v[234:235], v217 offset:62592
	ds_read_b64_tr_b16 v[236:237], v217 offset:65152
	ds_read_b64_tr_b16 v[238:239], v217 offset:62656
	ds_read_b64_tr_b16 v[240:241], v217 offset:65216
	s_waitcnt lgkmcnt(8)
	v_mfma_f32_32x32x16_bf16 v[48:63], v[88:91], v[152:155], v[48:63]
	v_add_f32_e32 v200, v201, v200
	v_mfma_f32_32x32x16_bf16 v[32:47], v[88:91], v[156:159], v[32:47]
	v_add_f32_e32 v184, v184, v200
	v_mfma_f32_32x32x16_bf16 v[16:31], v[88:91], v[160:163], v[16:31]
	v_mfma_f32_32x32x16_bf16 v[0:15], v[88:91], v[164:167], v[0:15]
	s_andn2_b64 vcc, exec, s[42:43]
	s_cbranch_vccz .LBB0_539
	s_branch .LBB0_540
.LBB0_552:
	v_exp_f32_e32 v104, v104
	v_exp_f32_e32 v105, v105
	v_add_f32_e32 v184, v104, v184
	v_exp_f32_e32 v106, v106
	v_add_f32_e32 v184, v105, v184
	v_exp_f32_e32 v107, v107
	v_add_f32_e32 v184, v106, v184
	v_exp_f32_e32 v108, v108
	v_add_f32_e32 v184, v107, v184
	v_exp_f32_e32 v109, v109
	v_add_f32_e32 v184, v108, v184
	v_exp_f32_e32 v110, v110
	v_add_f32_e32 v184, v109, v184
	v_exp_f32_e32 v111, v111
	v_add_f32_e32 v184, v110, v184
	v_add_f32_e32 v184, v111, v184
	v_cvt_pk_bf16_f32 v104, v104, v105
	v_cvt_pk_bf16_f32 v105, v106, v107
	v_cvt_pk_bf16_f32 v106, v108, v109
	v_cvt_pk_bf16_f32 v107, v110, v111
	s_nop 1
	v_mfma_f32_32x32x16_bf16 v[48:63], v[104:107], v[226:229], v[48:63]
	v_mfma_f32_32x32x16_bf16 v[32:47], v[104:107], v[230:233], v[32:47]
	v_mfma_f32_32x32x16_bf16 v[16:31], v[104:107], v[234:237], v[16:31]
	v_mfma_f32_32x32x16_bf16 v[0:15], v[104:107], v[238:241], v[0:15]
	s_nop 7
	s_nop 7
	v_mov_b32_e32 v64, v184
	s_nop 1
	v_permlane32_swap_b32_e32 v184, v64
	s_and_saveexec_b64 s[2:3], s[0:1]
	s_cbranch_execz .LBB0_518
	v_add_f32_e32 v64, v184, v64
	ds_write_b32 v216, v64 offset:6272
	s_branch .LBB0_518
